# prologue p->bf16 conversion loop unrolled x4 (was one HBM round trip per 16 bytes per thread)
# speedup vs baseline: 1.0111x; 1.0005x over previous
; __device__ __forceinline__ unsigned cvt_pk_bf16(float lo, float hi) { unsigned r; asm("v_cvt_pk_bf16_f32 %0, %1, %2" : "=v"(r) : "v"(lo), "v"(hi)); return r; }
; __global__ void __launch_bounds__(NWAVES * 64, 2) fwd_megakernel(Args args_unused) {
;     ...
;         const f32x4* p4 = (const f32x4*)A->in[1]; u32x2* pb = (u32x2*)WSP(WS_PB);
;         for (int idx = gtid; idx < DEPTH * NTOK * PLE / 4; idx += nthr) {
;             const f32x4 v = p4[idx]; u32x2 w; w.x = cvt_pk_bf16(v.x, v.y); w.y = cvt_pk_bf16(v.z, v.w); pb[idx] = w;
;         }
.LBB0_72:
	global_load_dwordx4 v[8:11], v[4:5], off
	v_lshl_add_u64 v[4:5], v[4:5], 0, s[2:3]
	global_load_dwordx4 v[12:15], v[4:5], off
	v_lshl_add_u64 v[4:5], v[4:5], 0, s[2:3]
	global_load_dwordx4 v[16:19], v[4:5], off
	v_lshl_add_u64 v[4:5], v[4:5], 0, s[2:3]
	global_load_dwordx4 v[20:23], v[4:5], off
	v_lshl_add_u64 v[4:5], v[4:5], 0, s[2:3]
	v_lshl_add_u32 v3, s6, 2, v3
	v_cmp_lt_i32_e32 vcc, s7, v3
	s_or_b64 s[18:19], vcc, s[18:19]
	s_waitcnt vmcnt(3)
	v_cvt_pk_bf16_f32 v8, v8, v9
	v_cvt_pk_bf16_f32 v9, v10, v11
	global_store_dwordx2 v[6:7], v[8:9], off
	v_lshl_add_u64 v[6:7], v[6:7], 0, s[16:17]
	s_waitcnt vmcnt(3)
	v_cvt_pk_bf16_f32 v12, v12, v13
	v_cvt_pk_bf16_f32 v13, v14, v15
	global_store_dwordx2 v[6:7], v[12:13], off
	v_lshl_add_u64 v[6:7], v[6:7], 0, s[16:17]
	s_waitcnt vmcnt(3)
	v_cvt_pk_bf16_f32 v16, v16, v17
	v_cvt_pk_bf16_f32 v17, v18, v19
	global_store_dwordx2 v[6:7], v[16:17], off
	v_lshl_add_u64 v[6:7], v[6:7], 0, s[16:17]
	s_waitcnt vmcnt(3)
	v_cvt_pk_bf16_f32 v20, v20, v21
	v_cvt_pk_bf16_f32 v21, v22, v23
	global_store_dwordx2 v[6:7], v[20:21], off
	v_lshl_add_u64 v[6:7], v[6:7], 0, s[16:17]
	s_andn2_b64 exec, exec, s[18:19]
	s_cbranch_execnz .LBB0_72
